# attention: kscale multiply deferred to tr_finish (v252-255), LDS fragment reads software-pipelined under QK/PV MFMAs; scan prologue C loads hoisted
# speedup vs baseline: 1.0099x; 1.0099x over previous
.LBB0_239:
	s_lshl_b32 s83, s48, 8
	v_readlane_b32 s0, v250, 48
	s_add_i32 s82, s83, s0
	v_add_lshl_u32 v0, v207, s82, 3
	v_and_b32_e32 v0, 0xffffff80, v0
	v_or_b32_e32 v2, s78, v0
	v_ashrrev_i32_e32 v3, 31, v2
	v_lshlrev_b64 v[4:5], 10, v[2:3]
	v_lshl_add_u64 v[4:5], v[170:171], 0, v[4:5]
	global_load_dwordx4 v[114:117], v[4:5], off
	global_load_dwordx4 v[118:121], v[4:5], off offset:32
	v_or_b32_e32 v4, s79, v0
	v_ashrrev_i32_e32 v5, 31, v4
	v_lshlrev_b64 v[4:5], 10, v[4:5]
	v_lshl_add_u64 v[4:5], v[170:171], 0, v[4:5]
	global_load_dwordx4 v[122:125], v[4:5], off
	global_load_dwordx4 v[126:129], v[4:5], off offset:32
	v_or_b32_e32 v4, 2, v2
	v_or_b32_e32 v2, 3, v2
	v_ashrrev_i32_e32 v5, 31, v4
	v_ashrrev_i32_e32 v3, 31, v2
	s_or_b32 s0, s83, 0xc0
	v_lshlrev_b64 v[4:5], 10, v[4:5]
	v_lshlrev_b64 v[2:3], 10, v[2:3]
	s_or_b32 s1, s0, s76
	v_lshl_add_u64 v[4:5], v[170:171], 0, v[4:5]
	v_lshl_add_u64 v[2:3], v[170:171], 0, v[2:3]
	v_add_lshl_u32 v0, v193, s1, 3
	global_load_dwordx4 v[130:133], v[4:5], off
	global_load_dwordx4 v[134:137], v[4:5], off offset:32
	global_load_dwordx4 v[138:141], v[2:3], off
	global_load_dwordx4 v[142:145], v[2:3], off offset:32
	v_and_or_b32 v2, v0, s66, v208
	v_add_lshl_u32 v0, s1, v184, 3
	v_ashrrev_i32_e32 v3, 31, v2
	v_and_or_b32 v6, v0, s66, v208
	v_lshlrev_b64 v[10:11], 10, v[2:3]
	v_lshlrev_b32_e32 v36, 1, v166
	v_ashrrev_i32_e32 v7, 31, v6
	v_or_b32_e32 v10, v10, v36
	v_lshlrev_b64 v[32:33], 10, v[6:7]
	v_lshl_add_u64 v[2:3], s[90:91], 0, v[10:11]
	v_or_b32_e32 v32, v32, v36
	v_lshl_add_u64 v[10:11], s[94:95], 0, v[10:11]
	global_load_dwordx4 v[12:15], v[10:11], off
	v_lshl_add_u64 v[10:11], s[94:95], 0, v[32:33]
	v_lshl_add_u64 v[6:7], s[90:91], 0, v[32:33]
	global_load_dwordx4 v[32:35], v[10:11], off
	s_and_b32 s1, s73, 1
	global_load_dwordx4 v[2:5], v[2:3], off
	v_mad_u32_u24 v0, s1, v202, 0
	global_load_dwordx4 v[6:9], v[6:7], off
	v_mad_u32_u24 v10, s1, v203, v0
	v_add3_u32 v11, v0, v185, v186
	s_add_i32 s1, s0, s77
	s_cmp_lt_i32 s71, 0xc000
	s_cselect_b32 s49, s71, -1
	s_cmp_gt_i32 s49, -1
	s_cselect_b64 s[62:63], -1, 0
	s_cmp_lt_i32 s49, 0
	v_lshlrev_b32_e32 v174, 2, v168
	s_waitcnt vmcnt(2)
	ds_write_b128 v11, v[32:35]
	ds_write_b128 v11, v[12:15] offset:8704
	v_add3_u32 v11, v10, v187, v186
	s_waitcnt vmcnt(0)
	ds_write_b128 v11, v[6:9] offset:34816
	ds_write_b128 v11, v[2:5] offset:45056
	v_add_u32_e32 v4, s1, v184
	v_add_u32_e32 v6, 32, v4
	v_lshlrev_b32_e32 v2, 3, v4
	v_lshlrev_b32_e32 v4, 3, v6
	v_and_or_b32 v4, v4, s66, v208
	v_and_or_b32 v2, v2, s66, v208
	v_ashrrev_i32_e32 v5, 31, v4
	v_ashrrev_i32_e32 v3, 31, v2
	v_lshlrev_b64 v[4:5], 9, v[4:5]
	v_lshlrev_b32_e32 v6, 5, v6
	v_and_or_b32 v4, v6, s75, v4
	v_lshlrev_b64 v[2:3], 10, v[2:3]
	v_or_b32_e32 v4, v4, v164
	v_or_b32_e32 v2, v2, v36
	v_lshl_add_u64 v[6:7], s[94:95], 0, v[2:3]
	v_lshlrev_b64 v[4:5], 1, v[4:5]
	v_lshl_add_u64 v[2:3], s[90:91], 0, v[2:3]
	s_waitcnt lgkmcnt(0)
	s_barrier
	global_load_dwordx4 v[146:149], v[6:7], off
	global_load_dwordx4 v[154:157], v[2:3], off
	v_lshl_add_u64 v[6:7], s[94:95], 0, v[4:5]
	v_lshl_add_u64 v[2:3], s[90:91], 0, v[4:5]
	global_load_dwordx4 v[150:153], v[6:7], off
	global_load_dwordx4 v[158:161], v[2:3], off
	s_cbranch_scc1 .LBB0_243
	v_sub_co_u32_e32 v2, vcc, s49, v204
	s_and_b64 s[64:65], vcc, exec
	s_cselect_b32 s1, s97, 0x100
	v_readfirstlane_b32 s64, v2
	v_cvt_f32_u32_e32 v2, s1
	s_cselect_b32 s2, s55, s57
	s_cselect_b32 s72, s54, s56
	s_cselect_b32 s64, s49, s64
	v_rcp_iflag_f32_e32 v2, v2
	s_sub_i32 s87, 0, s1
	s_abs_i32 s86, s64
	s_ashr_i32 s65, s64, 31
	v_mul_f32_e32 v2, 0x4f7ffffe, v2
	v_cvt_u32_f32_e32 v2, v2
	v_mov_b32_e32 v175, v1
	v_readfirstlane_b32 s89, v2
	s_mul_i32 s87, s87, s89
	s_mul_hi_u32 s87, s89, s87
	s_add_i32 s89, s89, s87
	s_mul_hi_u32 s87, s86, s89
	s_mul_i32 s89, s87, s1
	s_sub_i32 s86, s86, s89
	s_add_i32 s89, s87, 1
	s_sub_i32 s96, s86, s1
	s_cmp_ge_u32 s86, s1
	s_cselect_b32 s87, s89, s87
	s_cselect_b32 s86, s96, s86
	s_add_i32 s89, s87, 1
	s_cmp_ge_u32 s86, s1
	s_cselect_b32 s86, s89, s87
	s_xor_b32 s86, s86, s65
	s_sub_i32 s65, s86, s65
	s_mul_i32 s1, s65, s1
	s_sub_i32 s1, s64, s1
	s_lshl_b32 s64, s1, 5
	v_lshl_or_b32 v2, s65, 5, v178
	s_ashr_i32 s65, s64, 31
	s_lshl_b64 s[64:65], s[64:65], 2
	s_add_u32 s64, s72, s64
	s_addc_u32 s65, s2, s65
	s_and_b64 vcc, vcc, exec
	v_ashrrev_i32_e32 v3, 31, v2
	s_cselect_b32 s1, 12, 13
	v_lshl_add_u64 v[12:13], s[64:65], 0, v[174:175]
	v_lshlrev_b64 v[4:5], s1, v[2:3]
	v_lshl_add_u64 v[4:5], v[4:5], 2, v[12:13]
	global_load_dwordx4 v[16:19], v[4:5], off nt
	v_or_b32_e32 v4, 8, v2
	v_ashrrev_i32_e32 v5, 31, v4
	v_lshlrev_b64 v[6:7], s1, v[4:5]
	v_lshl_add_u64 v[6:7], v[6:7], 2, v[12:13]
	global_load_dwordx4 v[20:23], v[6:7], off nt
	v_or_b32_e32 v6, 16, v2
	v_ashrrev_i32_e32 v7, 31, v6
	v_lshlrev_b64 v[8:9], s1, v[6:7]
	v_lshl_add_u64 v[8:9], v[8:9], 2, v[12:13]
	global_load_dwordx4 v[24:27], v[8:9], off nt
	v_or_b32_e32 v8, 24, v2
	v_ashrrev_i32_e32 v9, 31, v8
	v_lshlrev_b64 v[14:15], s1, v[8:9]
	v_lshl_add_u64 v[12:13], v[14:15], 2, v[12:13]
	global_load_dwordx4 v[28:31], v[12:13], off nt
	s_cbranch_vccnz .LBB0_242
	v_lshl_add_u64 v[2:3], v[2:3], 2, s[40:41]
	v_lshl_add_u64 v[4:5], v[4:5], 2, s[40:41]
	v_lshl_add_u64 v[6:7], v[6:7], 2, s[40:41]
	v_lshl_add_u64 v[8:9], v[8:9], 2, s[40:41]
	global_load_dword v252, v[2:3], off
	global_load_dword v253, v[4:5], off
	global_load_dword v254, v[6:7], off
	global_load_dword v255, v[8:9], off

.LBB0_260:
	v_lshlrev_b32_e32 v0, 5, v197
	v_lshlrev_b32_e32 v2, 1, v197
	s_andn2_b64 vcc, exec, s[62:63]
	v_add_u32_e32 v228, 0x420, v206
	v_add_u32_e32 v229, 0x428, v206
	v_add_u32_e32 v230, 0x840, v206
	v_add_u32_e32 v231, 0x848, v206
	v_add_u32_e32 v232, 0xc60, v206
	v_add_u32_e32 v233, 0xc68, v206
	v_and_b32_e32 v234, 0x1e0, v0
	v_and_b32_e32 v235, 16, v2
	s_cbranch_vccnz .LBB0_262
	v_sub_co_u32_e32 v0, vcc, s49, v204
	s_and_b64 s[0:1], vcc, exec
	s_cselect_b32 s0, s97, 0x100
	v_readfirstlane_b32 s1, v0
	v_cvt_f32_u32_e32 v0, s0
	s_cselect_b32 s2, s70, s68
	s_cselect_b32 s62, s69, s67
	s_cselect_b32 s1, s49, s1
	s_cbranch_scc1 .Lcv_noscale_1
	s_waitcnt vmcnt(0)
	v_mul_f32_e32 v16, v16, v252
	v_mul_f32_e32 v17, v17, v252
	v_mul_f32_e32 v18, v18, v252
	v_mul_f32_e32 v19, v19, v252
	v_mul_f32_e32 v20, v20, v253
	v_mul_f32_e32 v21, v21, v253
	v_mul_f32_e32 v22, v22, v253
	v_mul_f32_e32 v23, v23, v253
	v_mul_f32_e32 v24, v24, v254
	v_mul_f32_e32 v25, v25, v254
	v_mul_f32_e32 v26, v26, v254
	v_mul_f32_e32 v27, v27, v254
	v_mul_f32_e32 v28, v28, v255
	v_mul_f32_e32 v29, v29, v255
	v_mul_f32_e32 v30, v30, v255
	v_mul_f32_e32 v31, v31, v255
.Lcv_noscale_1:
	v_rcp_iflag_f32_e32 v0, v0
	s_sub_i32 s64, 0, s0
	s_abs_i32 s63, s1
	s_ashr_i32 s49, s1, 31
	v_mul_f32_e32 v0, 0x4f7ffffe, v0
	v_cvt_u32_f32_e32 v0, v0
	s_waitcnt vmcnt(3)
	ds_write2_b32 v206, v16, v17 offset1:1
	ds_write2_b32 v206, v18, v19 offset0:2 offset1:3
	s_waitcnt vmcnt(2)
	ds_write2_b32 v228, v20, v21 offset1:1
	ds_write2_b32 v229, v22, v23 offset1:1
	s_waitcnt vmcnt(1)
	ds_write2_b32 v230, v24, v25 offset1:1
	ds_write2_b32 v231, v26, v27 offset1:1
	s_waitcnt vmcnt(0)
	ds_write2_b32 v232, v28, v29 offset1:1
	ds_write2_b32 v233, v30, v31 offset1:1
	s_waitcnt lgkmcnt(0)
	ds_read2_b32 v[2:3], v196 offset1:33
	ds_read2_b32 v[4:5], v196 offset0:66 offset1:99
	ds_read2_b32 v[6:7], v196 offset0:132 offset1:165
	ds_read2_b32 v[8:9], v196 offset0:198 offset1:231
	ds_read2_b32 v[10:11], v196 offset0:16 offset1:49
	ds_read2_b32 v[12:13], v196 offset0:82 offset1:115
	ds_read2_b32 v[14:15], v196 offset0:148 offset1:181
	ds_read2_b32 v[252:253], v196 offset0:214 offset1:247
	v_readfirstlane_b32 s65, v0
	s_mul_i32 s64, s64, s65
	s_mul_hi_u32 s64, s65, s64
	s_add_i32 s65, s65, s64
	s_mul_hi_u32 s64, s63, s65
	s_mul_i32 s65, s64, s0
	s_sub_i32 s63, s63, s65
	s_add_i32 s65, s64, 1
	s_sub_i32 s72, s63, s0
	s_cmp_ge_u32 s63, s0
	s_cselect_b32 s64, s65, s64
	s_cselect_b32 s63, s72, s63
	s_add_i32 s65, s64, 1
	s_cmp_ge_u32 s63, s0
	s_cselect_b32 s63, s65, s64
	s_xor_b32 s63, s63, s49
	s_sub_i32 s49, s63, s49
	s_mul_i32 s0, s49, s0
	s_sub_i32 s63, s1, s0
	s_lshl_b32 s64, s63, 5
	s_lshl_b32 s0, s63, 3
	s_andn2_b32 s0, s0, 63
	s_ashr_i32 s1, s49, 1
	v_or_b32_e32 v0, s64, v169
	s_add_i32 s0, s1, s0
	s_and_b32 s49, s49, 1
	v_lshrrev_b32_e32 v0, 3, v0
	s_ashr_i32 s1, s0, 31
	s_lshl_b32 s63, s63, 11
	v_and_or_b32 v0, v0, 14, s49
	s_and_b32 s63, s63, 0x2000
	s_lshl_b64 s[0:1], s[0:1], 15
	v_lshlrev_b32_e32 v0, 9, v0
	s_add_u32 s0, s62, s0
	v_or3_b32 v0, v0, v163, s63
	s_addc_u32 s1, s2, s1
	v_lshlrev_b32_e32 v0, 1, v0
	s_waitcnt lgkmcnt(4)
	v_cvt_pk_bf16_f32 v2, v2, v3
	v_cvt_pk_bf16_f32 v3, v4, v5
	v_cvt_pk_bf16_f32 v4, v6, v7
	v_cvt_pk_bf16_f32 v5, v8, v9
	global_store_dwordx4 v0, v[2:5], s[0:1]
	v_or_b32_e32 v0, s64, v197
	v_lshrrev_b32_e32 v0, 3, v0
	v_and_or_b32 v0, v0, 14, s49
	v_lshlrev_b32_e32 v0, 9, v0
	v_bitop3_b32 v6, v234, v235, v195 bitop3:0x36
	v_or3_b32 v0, v0, v6, s63
	v_lshlrev_b32_e32 v0, 1, v0
	s_waitcnt lgkmcnt(0)
	v_cvt_pk_bf16_f32 v10, v10, v11
	v_cvt_pk_bf16_f32 v11, v12, v13
	v_cvt_pk_bf16_f32 v12, v14, v15
	v_cvt_pk_bf16_f32 v13, v252, v253
	global_store_dwordx4 v0, v[10:13], s[0:1]
	s_waitcnt lgkmcnt(0)

.LBB0_270:
	s_cmp_lt_i32 s71, 0xc000
	s_cselect_b32 s89, s71, -1
	s_cmp_gt_i32 s89, -1
	s_cselect_b64 s[62:63], -1, 0
	s_cmp_lt_i32 s89, 0
	s_cbranch_scc1 .LBB0_274
	v_sub_co_u32_e32 v2, vcc, s89, v204
	s_and_b64 s[86:87], vcc, exec
	s_cselect_b32 s86, s97, 0x100
	v_readfirstlane_b32 s87, v2
	v_cvt_f32_u32_e32 v2, s86
	s_cselect_b32 s96, s55, s57
	s_cselect_b32 s33, s54, s56
	s_cselect_b32 s87, s89, s87
	v_rcp_iflag_f32_e32 v2, v2
	s_sub_i32 s84, 0, s86
	s_abs_i32 s53, s87
	s_ashr_i32 s52, s87, 31
	v_mul_f32_e32 v2, 0x4f7ffffe, v2
	v_cvt_u32_f32_e32 v2, v2
	v_mov_b32_e32 v175, v1
	v_readfirstlane_b32 s85, v2
	s_mul_i32 s84, s84, s85
	s_mul_hi_u32 s84, s85, s84
	s_add_i32 s85, s85, s84
	s_mul_hi_u32 s84, s53, s85
	s_mul_i32 s85, s84, s86
	s_sub_i32 s53, s53, s85
	s_add_i32 s85, s84, 1
	s_sub_i32 s60, s53, s86
	s_cmp_ge_u32 s53, s86
	s_cselect_b32 s61, s85, s84
	s_cselect_b32 s53, s60, s53
	s_add_i32 s60, s61, 1
	s_cmp_ge_u32 s53, s86
	s_cselect_b32 s53, s60, s61
	s_xor_b32 s53, s53, s52
	s_sub_i32 s52, s53, s52
	s_mul_i32 s53, s52, s86
	s_sub_i32 s53, s87, s53
	s_lshl_b32 s86, s53, 5
	s_ashr_i32 s87, s86, 31
	s_lshl_b64 s[86:87], s[86:87], 2
	s_add_u32 s86, s33, s86
	s_addc_u32 s87, s96, s87
	v_lshl_or_b32 v2, s52, 5, v178
	s_and_b64 vcc, vcc, exec
	v_ashrrev_i32_e32 v3, 31, v2
	s_cselect_b32 s33, 12, 13
	v_lshl_add_u64 v[12:13], s[86:87], 0, v[174:175]
	v_lshlrev_b64 v[4:5], s33, v[2:3]
	v_lshl_add_u64 v[4:5], v[4:5], 2, v[12:13]
	global_load_dwordx4 v[16:19], v[4:5], off nt
	v_or_b32_e32 v4, 8, v2
	v_ashrrev_i32_e32 v5, 31, v4
	v_lshlrev_b64 v[6:7], s33, v[4:5]
	v_lshl_add_u64 v[6:7], v[6:7], 2, v[12:13]
	global_load_dwordx4 v[20:23], v[6:7], off nt
	v_or_b32_e32 v6, 16, v2
	v_ashrrev_i32_e32 v7, 31, v6
	v_lshlrev_b64 v[8:9], s33, v[6:7]
	v_lshl_add_u64 v[8:9], v[8:9], 2, v[12:13]
	global_load_dwordx4 v[24:27], v[8:9], off nt
	v_or_b32_e32 v8, 24, v2
	v_ashrrev_i32_e32 v9, 31, v8
	v_lshlrev_b64 v[14:15], s33, v[8:9]
	v_lshl_add_u64 v[12:13], v[14:15], 2, v[12:13]
	global_load_dwordx4 v[28:31], v[12:13], off nt
	s_cbranch_vccnz .LBB0_273
	v_lshl_add_u64 v[2:3], v[2:3], 2, s[40:41]
	v_lshl_add_u64 v[4:5], v[4:5], 2, s[40:41]
	v_lshl_add_u64 v[6:7], v[6:7], 2, s[40:41]
	v_lshl_add_u64 v[8:9], v[8:9], 2, s[40:41]
	global_load_dword v252, v[2:3], off
	global_load_dword v253, v[4:5], off
	global_load_dword v254, v[6:7], off
	global_load_dword v255, v[8:9], off

.LBB0_274:
	s_add_i32 s86, s83, s72
	s_addk_i32 s86, 0x80
	s_cmp_gt_i32 s86, s82
	s_cselect_b64 vcc, -1, 0
	s_or_b64 s[64:65], vcc, s[64:65]
	s_and_b64 vcc, exec, s[64:65]
	s_cbranch_vccnz .LBB0_288
	v_add_u32_e32 v0, v0, v188
	v_add_u32_e32 v175, v10, v190
	s_cmp_ge_u32 s86, s82
	v_add_u32_e32 v176, v0, v162
	s_cbranch_scc1 .LBB0_282
	ds_read_b128 v[2:5], v176 offset:8704
	ds_read_b128 v[6:9], v176 offset:8736
	ds_read_b128 v[10:13], v176 offset:8768
	s_cmp_eq_u32 s74, s72
	s_cselect_b64 s[64:65], -1, 0
	s_cmp_lg_u32 s74, s72
	s_waitcnt lgkmcnt(2)
	v_mfma_f32_32x32x16_bf16 v[96:111], v[2:5], v[114:117], 0
	ds_read_b128 v[2:5], v176 offset:8800
	s_waitcnt lgkmcnt(2)
	v_mfma_f32_32x32x16_bf16 v[96:111], v[6:9], v[118:121], v[96:111]
	ds_read_b128 v[6:9], v176 offset:8832
	s_waitcnt lgkmcnt(2)
	v_mfma_f32_32x32x16_bf16 v[96:111], v[10:13], v[122:125], v[96:111]
	ds_read_b128 v[10:13], v176 offset:8864
	s_waitcnt lgkmcnt(2)
	v_mfma_f32_32x32x16_bf16 v[96:111], v[2:5], v[126:129], v[96:111]
	ds_read_b128 v[2:5], v176 offset:8896
	s_waitcnt lgkmcnt(2)
	v_mfma_f32_32x32x16_bf16 v[96:111], v[6:9], v[130:133], v[96:111]
	ds_read_b128 v[6:9], v176 offset:8928
	s_waitcnt lgkmcnt(2)
	v_mfma_f32_32x32x16_bf16 v[96:111], v[10:13], v[134:137], v[96:111]
	s_waitcnt lgkmcnt(1)
	v_mfma_f32_32x32x16_bf16 v[96:111], v[2:5], v[138:141], v[96:111]
	s_waitcnt lgkmcnt(0)
	v_mfma_f32_32x32x16_bf16 v[96:111], v[6:9], v[142:145], v[96:111]
	s_nop 11
	v_exp_f32_e32 v0, v96
	v_exp_f32_e32 v2, v97
	v_exp_f32_e32 v3, v98
	v_exp_f32_e32 v4, v99
	v_exp_f32_e32 v5, v100
	v_exp_f32_e32 v6, v101
	v_exp_f32_e32 v7, v102
	v_exp_f32_e32 v8, v103
	v_exp_f32_e32 v9, v104
	v_exp_f32_e32 v10, v105
	v_exp_f32_e32 v11, v106
	v_exp_f32_e32 v12, v107
	v_exp_f32_e32 v13, v108
	v_exp_f32_e32 v14, v109
	v_exp_f32_e32 v15, v110
	v_exp_f32_e32 v112, v111
	v_add_f32_e32 v0, 1.0, v0
	v_add_f32_e32 v2, 1.0, v2
	v_add_f32_e32 v3, 1.0, v3
	v_add_f32_e32 v4, 1.0, v4
	v_add_f32_e32 v113, 1.0, v5
	v_add_f32_e32 v6, 1.0, v6
	v_add_f32_e32 v177, 1.0, v7
	v_add_f32_e32 v8, 1.0, v8
	v_add_f32_e32 v9, 1.0, v9
	v_add_f32_e32 v10, 1.0, v10
	v_add_f32_e32 v11, 1.0, v11
	v_add_f32_e32 v12, 1.0, v12
	v_add_f32_e32 v13, 1.0, v13
	v_add_f32_e32 v14, 1.0, v14
	v_add_f32_e32 v238, 1.0, v15
	v_add_f32_e32 v239, 1.0, v112
	v_log_f32_e32 v112, v0
	v_log_f32_e32 v5, v2
	v_log_f32_e32 v2, v3
	v_log_f32_e32 v3, v4
	v_log_f32_e32 v4, v113
	v_log_f32_e32 v7, v6
	v_log_f32_e32 v6, v177
	v_log_f32_e32 v15, v8
	v_log_f32_e32 v8, v9
	v_log_f32_e32 v9, v10
	v_log_f32_e32 v10, v11
	v_log_f32_e32 v11, v12
	v_log_f32_e32 v12, v13
	v_log_f32_e32 v13, v14
	v_log_f32_e32 v14, v238
	v_log_f32_e32 v0, v239
	s_cbranch_scc1 .LBB0_278
	v_cndmask_b32_e64 v112, 0, -v112, s[6:7]
	v_cndmask_b32_e64 v5, 0, -v5, s[8:9]
	v_cndmask_b32_e64 v2, 0, -v2, s[10:11]
	v_cndmask_b32_e64 v3, 0, -v3, s[12:13]
	v_cndmask_b32_e64 v4, 0, -v4, s[14:15]
	v_cndmask_b32_e64 v7, 0, -v7, s[16:17]
	v_cndmask_b32_e64 v6, 0, -v6, s[18:19]
	v_cndmask_b32_e64 v113, 0, -v15, s[20:21]
	v_cndmask_b32_e64 v8, 0, -v8, s[22:23]
	v_cndmask_b32_e64 v9, 0, -v9, s[24:25]
	v_cndmask_b32_e64 v10, 0, -v10, s[26:27]
	v_cndmask_b32_e64 v11, 0, -v11, s[28:29]
	v_cndmask_b32_e64 v12, 0, -v12, s[30:31]
	v_cndmask_b32_e64 v13, 0, -v13, s[34:35]
	v_cndmask_b32_e64 v14, 0, -v14, s[36:37]
	v_cndmask_b32_e64 v15, 0, -v0, s[38:39]
	s_branch .LBB0_279

.LBB0_281:
	v_cvt_pk_bf16_f32 v98, v0, v5
	v_add_u32_e32 v0, v175, v191
	v_cvt_pk_bf16_f32 v99, v2, v3
	v_cvt_pk_bf16_f32 v100, v4, v7
	v_cvt_pk_bf16_f32 v101, v6, v97
	v_cvt_pk_bf16_f32 v2, v8, v9
	v_cvt_pk_bf16_f32 v3, v10, v11
	v_cvt_pk_bf16_f32 v4, v12, v13
	v_cvt_pk_bf16_f32 v5, v14, v15
	ds_read_b64_tr_b16 v[6:7], v0 offset:45056
	ds_read_b64_tr_b16 v[8:9], v0 offset:47616
	ds_read_b64_tr_b16 v[10:11], v0 offset:50176
	ds_read_b64_tr_b16 v[12:13], v0 offset:52736
	ds_read_b64_tr_b16 v[104:105], v0 offset:45120
	ds_read_b64_tr_b16 v[106:107], v0 offset:47680
	ds_read_b64_tr_b16 v[108:109], v0 offset:50240
	ds_read_b64_tr_b16 v[110:111], v0 offset:52800
	s_waitcnt lgkmcnt(6)
	v_mfma_f32_32x32x16_bf16 v[80:95], v[6:9], v[98:101], v[80:95]
	v_add_f32_e32 v96, v177, v238
	v_add_f32_e32 v96, v96, v239
	v_add_f32_e32 v227, v227, v96
	s_waitcnt lgkmcnt(4)
	v_mfma_f32_32x32x16_bf16 v[80:95], v[10:13], v[2:5], v[80:95]
	ds_read_b64_tr_b16 v[6:7], v0 offset:45184
	ds_read_b64_tr_b16 v[8:9], v0 offset:47744
	ds_read_b64_tr_b16 v[10:11], v0 offset:50304
	ds_read_b64_tr_b16 v[12:13], v0 offset:52864
	s_waitcnt lgkmcnt(6)
	v_mfma_f32_32x32x16_bf16 v[64:79], v[104:107], v[98:101], v[64:79]
	s_waitcnt lgkmcnt(4)
	v_mfma_f32_32x32x16_bf16 v[64:79], v[108:111], v[2:5], v[64:79]
	ds_read_b64_tr_b16 v[104:105], v0 offset:45248
	ds_read_b64_tr_b16 v[106:107], v0 offset:47808
	ds_read_b64_tr_b16 v[108:109], v0 offset:50368
	ds_read_b64_tr_b16 v[110:111], v0 offset:52928
	s_waitcnt lgkmcnt(6)
	v_mfma_f32_32x32x16_bf16 v[48:63], v[6:9], v[98:101], v[48:63]
	s_waitcnt lgkmcnt(4)
	v_mfma_f32_32x32x16_bf16 v[48:63], v[10:13], v[2:5], v[48:63]
	s_waitcnt lgkmcnt(2)
	v_mfma_f32_32x32x16_bf16 v[32:47], v[104:107], v[98:101], v[32:47]
	s_waitcnt lgkmcnt(0)
	v_mfma_f32_32x32x16_bf16 v[32:47], v[108:111], v[2:5], v[32:47]
.LBB0_282:
	ds_read_b128 v[2:5], v176
	ds_read_b128 v[6:9], v176 offset:32
	ds_read_b128 v[10:13], v176 offset:64
	s_cmp_eq_u32 s3, s72
	s_cselect_b64 s[64:65], -1, 0
	s_cmp_lg_u32 s3, s72
	s_waitcnt lgkmcnt(2)
	v_mfma_f32_32x32x16_bf16 v[96:111], v[2:5], v[114:117], 0
	ds_read_b128 v[2:5], v176 offset:96
	s_waitcnt lgkmcnt(2)
	v_mfma_f32_32x32x16_bf16 v[96:111], v[6:9], v[118:121], v[96:111]
	ds_read_b128 v[6:9], v176 offset:128
	s_waitcnt lgkmcnt(2)
	v_mfma_f32_32x32x16_bf16 v[96:111], v[10:13], v[122:125], v[96:111]
	ds_read_b128 v[10:13], v176 offset:160
	s_waitcnt lgkmcnt(2)
	v_mfma_f32_32x32x16_bf16 v[96:111], v[2:5], v[126:129], v[96:111]
	ds_read_b128 v[2:5], v176 offset:192
	s_waitcnt lgkmcnt(2)
	v_mfma_f32_32x32x16_bf16 v[96:111], v[6:9], v[130:133], v[96:111]
	ds_read_b128 v[6:9], v176 offset:224
	s_waitcnt lgkmcnt(2)
	v_mfma_f32_32x32x16_bf16 v[96:111], v[10:13], v[134:137], v[96:111]
	s_waitcnt lgkmcnt(1)
	v_mfma_f32_32x32x16_bf16 v[96:111], v[2:5], v[138:141], v[96:111]
	s_waitcnt lgkmcnt(0)
	v_mfma_f32_32x32x16_bf16 v[96:111], v[6:9], v[142:145], v[96:111]
	s_nop 11
	v_exp_f32_e32 v0, v96
	v_exp_f32_e32 v2, v97
	v_exp_f32_e32 v3, v98
	v_exp_f32_e32 v4, v99
	v_exp_f32_e32 v5, v100
	v_exp_f32_e32 v6, v101
	v_exp_f32_e32 v7, v102
	v_exp_f32_e32 v8, v103
	v_exp_f32_e32 v9, v104
	v_exp_f32_e32 v10, v105
	v_exp_f32_e32 v11, v106
	v_exp_f32_e32 v12, v107
	v_exp_f32_e32 v13, v108
	v_exp_f32_e32 v14, v109
	v_exp_f32_e32 v15, v110
	v_exp_f32_e32 v112, v111
	v_add_f32_e32 v0, 1.0, v0
	v_add_f32_e32 v2, 1.0, v2
	v_add_f32_e32 v3, 1.0, v3
	v_add_f32_e32 v113, 1.0, v4
	v_add_f32_e32 v176, 1.0, v5
	v_add_f32_e32 v177, 1.0, v6
	v_add_f32_e32 v238, 1.0, v7
	v_add_f32_e32 v8, 1.0, v8
	v_add_f32_e32 v9, 1.0, v9
	v_add_f32_e32 v239, 1.0, v10
	v_add_f32_e32 v240, 1.0, v11
	v_add_f32_e32 v241, 1.0, v12
	v_add_f32_e32 v242, 1.0, v13
	v_add_f32_e32 v243, 1.0, v14
	v_add_f32_e32 v244, 1.0, v15
	v_add_f32_e32 v245, 1.0, v112
	v_log_f32_e32 v4, v0
	v_log_f32_e32 v6, v2
	v_log_f32_e32 v7, v3
	v_log_f32_e32 v5, v113
	v_log_f32_e32 v10, v176
	v_log_f32_e32 v12, v177
	v_log_f32_e32 v13, v238
	v_log_f32_e32 v11, v8
	v_log_f32_e32 v8, v9
	v_log_f32_e32 v112, v239
	v_log_f32_e32 v15, v240
	v_log_f32_e32 v9, v241
	v_log_f32_e32 v14, v242
	v_log_f32_e32 v3, v243
	v_log_f32_e32 v2, v244
	v_log_f32_e32 v0, v245
	s_cbranch_scc1 .LBB0_284
	v_cndmask_b32_e64 v4, 0, -v4, s[6:7]
	v_cndmask_b32_e64 v6, 0, -v6, s[8:9]
	v_cndmask_b32_e64 v7, 0, -v7, s[10:11]
	v_cndmask_b32_e64 v5, 0, -v5, s[12:13]
	v_cndmask_b32_e64 v10, 0, -v10, s[14:15]
	v_cndmask_b32_e64 v12, 0, -v12, s[16:17]
	v_cndmask_b32_e64 v13, 0, -v13, s[18:19]
	v_cndmask_b32_e64 v11, 0, -v11, s[20:21]
	v_cndmask_b32_e64 v8, 0, -v8, s[22:23]
	v_cndmask_b32_e64 v176, 0, -v112, s[24:25]
	v_cndmask_b32_e64 v177, 0, -v15, s[26:27]
	v_cndmask_b32_e64 v9, 0, -v9, s[28:29]
	v_cndmask_b32_e64 v14, 0, -v14, s[30:31]
	v_cndmask_b32_e64 v112, 0, -v3, s[34:35]
	v_cndmask_b32_e64 v113, 0, -v2, s[36:37]
	v_cndmask_b32_e64 v15, 0, -v0, s[38:39]
	s_branch .LBB0_285

.LBB0_287:
	v_cvt_pk_bf16_f32 v98, v0, v5
	v_add_u32_e32 v0, v175, v191
	v_cvt_pk_bf16_f32 v99, v2, v3
	v_cvt_pk_bf16_f32 v100, v4, v13
	v_cvt_pk_bf16_f32 v101, v6, v7
	v_cvt_pk_bf16_f32 v2, v8, v9
	v_cvt_pk_bf16_f32 v3, v10, v11
	v_cvt_pk_bf16_f32 v4, v12, v97
	v_cvt_pk_bf16_f32 v5, v14, v15
	ds_read_b64_tr_b16 v[6:7], v0 offset:34816
	ds_read_b64_tr_b16 v[8:9], v0 offset:37376
	ds_read_b64_tr_b16 v[10:11], v0 offset:39936
	ds_read_b64_tr_b16 v[12:13], v0 offset:42496
	ds_read_b64_tr_b16 v[104:105], v0 offset:34880
	ds_read_b64_tr_b16 v[106:107], v0 offset:37440
	ds_read_b64_tr_b16 v[108:109], v0 offset:40000
	ds_read_b64_tr_b16 v[110:111], v0 offset:42560
	s_waitcnt lgkmcnt(6)
	v_mfma_f32_32x32x16_bf16 v[80:95], v[6:9], v[98:101], v[80:95]
	v_add_f32_e32 v96, v238, v239
	v_add_f32_e32 v96, v96, v240
	v_add_f32_e32 v227, v227, v96
	s_waitcnt lgkmcnt(4)
	v_mfma_f32_32x32x16_bf16 v[80:95], v[10:13], v[2:5], v[80:95]
	ds_read_b64_tr_b16 v[6:7], v0 offset:34944
	ds_read_b64_tr_b16 v[8:9], v0 offset:37504
	ds_read_b64_tr_b16 v[10:11], v0 offset:40064
	ds_read_b64_tr_b16 v[12:13], v0 offset:42624
	s_waitcnt lgkmcnt(6)
	v_mfma_f32_32x32x16_bf16 v[64:79], v[104:107], v[98:101], v[64:79]
	s_waitcnt lgkmcnt(4)
	v_mfma_f32_32x32x16_bf16 v[64:79], v[108:111], v[2:5], v[64:79]
	ds_read_b64_tr_b16 v[104:105], v0 offset:35008
	ds_read_b64_tr_b16 v[106:107], v0 offset:37568
	ds_read_b64_tr_b16 v[108:109], v0 offset:40128
	ds_read_b64_tr_b16 v[110:111], v0 offset:42688
	s_waitcnt lgkmcnt(6)
	v_mfma_f32_32x32x16_bf16 v[48:63], v[6:9], v[98:101], v[48:63]
	s_waitcnt lgkmcnt(4)
	v_mfma_f32_32x32x16_bf16 v[48:63], v[10:13], v[2:5], v[48:63]
	s_waitcnt lgkmcnt(2)
	v_mfma_f32_32x32x16_bf16 v[32:47], v[104:107], v[98:101], v[32:47]
	s_waitcnt lgkmcnt(0)
	v_mfma_f32_32x32x16_bf16 v[32:47], v[108:111], v[2:5], v[32:47]
.LBB0_288:
	s_andn2_b64 vcc, exec, s[62:63]
	s_cbranch_vccnz .LBB0_290
	v_sub_co_u32_e32 v0, vcc, s89, v204
	s_and_b64 s[62:63], vcc, exec
	s_cselect_b32 s33, s97, 0x100
	v_readfirstlane_b32 s60, v0
	v_cvt_f32_u32_e32 v0, s33
	s_cselect_b32 s52, s70, s68
	s_cselect_b32 s53, s69, s67
	s_cselect_b32 s60, s89, s60
	s_cbranch_scc1 .Lcv_noscale_2
	s_waitcnt vmcnt(0)
	v_mul_f32_e32 v16, v16, v252
	v_mul_f32_e32 v17, v17, v252
	v_mul_f32_e32 v18, v18, v252
	v_mul_f32_e32 v19, v19, v252
	v_mul_f32_e32 v20, v20, v253
	v_mul_f32_e32 v21, v21, v253
	v_mul_f32_e32 v22, v22, v253
	v_mul_f32_e32 v23, v23, v253
	v_mul_f32_e32 v24, v24, v254
	v_mul_f32_e32 v25, v25, v254
	v_mul_f32_e32 v26, v26, v254
	v_mul_f32_e32 v27, v27, v254
	v_mul_f32_e32 v28, v28, v255
	v_mul_f32_e32 v29, v29, v255
	v_mul_f32_e32 v30, v30, v255
	v_mul_f32_e32 v31, v31, v255
.Lcv_noscale_2:
	v_rcp_iflag_f32_e32 v0, v0
	s_sub_i32 s63, 0, s33
	s_abs_i32 s62, s60
	s_ashr_i32 s61, s60, 31
	v_mul_f32_e32 v0, 0x4f7ffffe, v0
	v_cvt_u32_f32_e32 v0, v0
	s_waitcnt vmcnt(3)
	ds_write2_b32 v206, v16, v17 offset1:1
	ds_write2_b32 v206, v18, v19 offset0:2 offset1:3
	s_waitcnt vmcnt(2)
	ds_write2_b32 v228, v20, v21 offset1:1
	ds_write2_b32 v229, v22, v23 offset1:1
	s_waitcnt vmcnt(1)
	ds_write2_b32 v230, v24, v25 offset1:1
	ds_write2_b32 v231, v26, v27 offset1:1
	s_waitcnt vmcnt(0)
	ds_write2_b32 v232, v28, v29 offset1:1
	ds_write2_b32 v233, v30, v31 offset1:1
	s_waitcnt lgkmcnt(0)
	ds_read2_b32 v[2:3], v196 offset1:33
	ds_read2_b32 v[4:5], v196 offset0:66 offset1:99
	ds_read2_b32 v[6:7], v196 offset0:132 offset1:165
	ds_read2_b32 v[8:9], v196 offset0:198 offset1:231
	ds_read2_b32 v[10:11], v196 offset0:16 offset1:49
	ds_read2_b32 v[12:13], v196 offset0:82 offset1:115
	ds_read2_b32 v[14:15], v196 offset0:148 offset1:181
	ds_read2_b32 v[252:253], v196 offset0:214 offset1:247
	v_readfirstlane_b32 s64, v0
	s_mul_i32 s63, s63, s64
	s_mul_hi_u32 s63, s64, s63
	s_add_i32 s64, s64, s63
	s_mul_hi_u32 s63, s62, s64
	s_mul_i32 s64, s63, s33
	s_sub_i32 s62, s62, s64
	s_add_i32 s64, s63, 1
	s_sub_i32 s65, s62, s33
	s_cmp_ge_u32 s62, s33
	s_cselect_b32 s63, s64, s63
	s_cselect_b32 s62, s65, s62
	s_add_i32 s64, s63, 1
	s_cmp_ge_u32 s62, s33
	s_cselect_b32 s62, s64, s63
	s_xor_b32 s62, s62, s61
	s_sub_i32 s61, s62, s61
	s_mul_i32 s33, s61, s33
	s_sub_i32 s33, s60, s33
	s_lshl_b32 s60, s33, 5
	s_lshl_b32 s62, s33, 3
	s_andn2_b32 s62, s62, 63
	s_ashr_i32 s63, s61, 1
	v_or_b32_e32 v0, s60, v169
	s_add_i32 s62, s63, s62
	s_and_b32 s61, s61, 1
	v_lshrrev_b32_e32 v0, 3, v0
	s_ashr_i32 s63, s62, 31
	s_lshl_b32 s33, s33, 11
	v_and_or_b32 v0, v0, 14, s61
	s_and_b32 s33, s33, 0x2000
	s_lshl_b64 s[62:63], s[62:63], 15
	v_lshlrev_b32_e32 v0, 9, v0
	s_add_u32 s62, s53, s62
	v_or3_b32 v0, v0, v163, s33
	s_addc_u32 s63, s52, s63
	v_lshlrev_b32_e32 v0, 1, v0
	s_waitcnt lgkmcnt(4)
	v_cvt_pk_bf16_f32 v2, v2, v3
	v_cvt_pk_bf16_f32 v3, v4, v5
	v_cvt_pk_bf16_f32 v4, v6, v7
	v_cvt_pk_bf16_f32 v5, v8, v9
	global_store_dwordx4 v0, v[2:5], s[62:63]
	v_or_b32_e32 v0, s60, v197
	v_lshrrev_b32_e32 v0, 3, v0
	v_and_or_b32 v0, v0, 14, s61
	v_lshlrev_b32_e32 v0, 9, v0
	v_bitop3_b32 v6, v234, v235, v195 bitop3:0x36
	v_or3_b32 v0, v0, v6, s33
	v_lshlrev_b32_e32 v0, 1, v0
	s_waitcnt lgkmcnt(0)
	v_cvt_pk_bf16_f32 v10, v10, v11
	v_cvt_pk_bf16_f32 v11, v12, v13
	v_cvt_pk_bf16_f32 v12, v14, v15
	v_cvt_pk_bf16_f32 v13, v252, v253
	global_store_dwordx4 v0, v[10:13], s[62:63]
	s_waitcnt lgkmcnt(0)

.LBB0_563:
	s_and_b32 s13, s6, 0xff
	s_lshl_b32 s0, s13, 2
	v_mov_b32_e32 v0, s0
	global_load_dword v2, v0, s[38:39]
	s_lshl_b32 s4, s13, 6
	v_or_b32_e32 v0, s4, v174
	v_lshlrev_b32_e32 v3, 2, v0
	global_load_dword v21, v3, s[58:59]
	global_load_dword v20, v3, s[36:37]
	s_and_b32 s2, s10, 0x1800
	v_or_b32_e32 v1, s2, v182
	v_lshlrev_b32_e32 v1, 3, v1
	s_bfe_u32 s0, s12, 0x70001
	v_and_b32_e32 v1, 0xc180, v1
	v_or_b32_e32 v1, s0, v1
	v_lshlrev_b32_e32 v132, 10, v1
	v_lshl_add_u64 v[150:151], v[144:145], 0, v[132:133]
	v_lshl_add_u64 v[152:153], v[146:147], 0, v[132:133]
	v_lshl_add_u64 v[154:155], v[148:149], 0, v[132:133]
	v_lshlrev_b32_e32 v132, 6, v0
	v_lshl_add_u64 v[0:1], v[136:137], 0, v[132:133]
	global_load_dwordx4 v[4:7], v[0:1], off
	global_load_dwordx4 v[8:11], v[0:1], off offset:16
	v_lshl_add_u64 v[0:1], v[134:135], 0, v[132:133]
	global_load_dwordx4 v[12:15], v[0:1], off
	global_load_dwordx4 v[16:19], v[0:1], off offset:16
	v_or_b32_e32 v0, s4, v173
	v_lshlrev_b32_e32 v22, 2, v0
	v_or_b32_e32 v132, 0x800, v132
	s_bfe_u32 s16, s6, 0x70001
	v_mov_b32_e32 v188, 0
	v_mov_b32_e32 v189, v133
	s_waitcnt vmcnt(6)
	v_mul_f32_e32 v0, 0x3fb8aa3b, v2
	v_exp_f32_e32 v0, v0
	global_load_dword v2, v22, s[58:59]
	global_load_dword v1, v22, s[36:37]
	s_waitcnt vmcnt(7)
	v_mov_b32_e32 v22, v21
	v_mov_b32_e32 v25, v21
	v_mul_f32_e32 v23, v0, v21
	s_waitcnt vmcnt(6)
	v_mul_f32_e32 v24, v0, v20
	v_mul_f32_e32 v23, 0x3fb8aa3b, v23
	v_mul_f32_e32 v24, 0.15915494, v24
	v_exp_f32_e32 v23, v23
	v_sin_f32_e32 v26, v24
	v_cos_f32_e32 v24, v24
	v_mov_b32_e32 v27, v20
	v_mul_f32_e32 v28, v23, v26
	v_fma_f32 v29, v23, v24, -1.0
	v_mov_b32_e32 v24, v28
	v_mov_b32_e32 v26, v29
	v_pk_mul_f32 v[30:31], v[20:21], v[28:29]
	v_pk_mul_f32 v[22:23], v[22:23], v[24:25] op_sel_hi:[0,1]
	v_pk_mul_f32 v[20:21], v[20:21], v[26:27] op_sel_hi:[0,1]
	v_add_f32_e32 v28, v30, v31
	v_add_f32_e32 v21, v23, v21
	v_sub_f32_e32 v22, v22, v20
	v_div_scale_f32 v20, s[0:1], v21, v21, v28
	v_div_scale_f32 v24, s[0:1], v21, v21, v22
	v_rcp_f32_e32 v25, v20
	v_rcp_f32_e32 v26, v24
	v_div_scale_f32 v23, vcc, v28, v21, v28
	v_fma_f32 v29, -v20, v25, 1.0
	v_fma_f32 v30, -v24, v26, 1.0
	v_fmac_f32_e32 v25, v29, v25
	v_div_scale_f32 v27, s[0:1], v22, v21, v22
	v_fmac_f32_e32 v26, v30, v26
	v_mul_f32_e32 v29, v23, v25
	v_mul_f32_e32 v30, v27, v26
	v_fma_f32 v31, -v20, v29, v23
	v_fma_f32 v32, -v24, v30, v27
	v_fmac_f32_e32 v29, v31, v25
	v_fmac_f32_e32 v30, v32, v26
	v_fma_f32 v20, -v20, v29, v23
	v_fma_f32 v23, -v24, v30, v27
	v_div_fmas_f32 v20, v20, v25, v29
	s_mov_b64 vcc, s[0:1]
	v_div_fmas_f32 v23, v23, v26, v30
	v_div_fixup_f32 v22, v23, v21, v22
	v_div_fixup_f32 v20, v20, v21, v28
	s_waitcnt vmcnt(5)
	v_pk_mul_f32 v[24:25], v[4:5], v[22:23] op_sel_hi:[1,0]
	v_pk_mul_f32 v[26:27], v[6:7], v[22:23] op_sel_hi:[1,0]
	s_waitcnt vmcnt(4)
	v_pk_mul_f32 v[28:29], v[8:9], v[22:23] op_sel_hi:[1,0]
	v_pk_mul_f32 v[30:31], v[10:11], v[22:23] op_sel_hi:[1,0]
	s_waitcnt vmcnt(3)
	v_pk_mul_f32 v[32:33], v[12:13], v[22:23] op_sel_hi:[1,0]
	v_pk_mul_f32 v[34:35], v[14:15], v[22:23] op_sel_hi:[1,0]
	s_waitcnt vmcnt(2)
	v_pk_mul_f32 v[36:37], v[16:17], v[22:23] op_sel_hi:[1,0]
	v_pk_mul_f32 v[22:23], v[18:19], v[22:23] op_sel_hi:[1,0]
	v_pk_fma_f32 v[14:15], v[14:15], v[20:21], v[26:27] op_sel_hi:[1,0,1] neg_lo:[0,0,1] neg_hi:[0,0,1]
	v_pk_fma_f32 v[12:13], v[12:13], v[20:21], v[24:25] op_sel_hi:[1,0,1] neg_lo:[0,0,1] neg_hi:[0,0,1]
	v_pk_fma_f32 v[18:19], v[18:19], v[20:21], v[30:31] op_sel_hi:[1,0,1] neg_lo:[0,0,1] neg_hi:[0,0,1]
	v_pk_fma_f32 v[16:17], v[16:17], v[20:21], v[28:29] op_sel_hi:[1,0,1] neg_lo:[0,0,1] neg_hi:[0,0,1]
	v_pk_fma_f32 v[6:7], v[6:7], v[20:21], v[34:35] op_sel_hi:[1,0,1]
	v_pk_fma_f32 v[4:5], v[4:5], v[20:21], v[32:33] op_sel_hi:[1,0,1]
	v_pk_fma_f32 v[10:11], v[10:11], v[20:21], v[22:23] op_sel_hi:[1,0,1]
	v_pk_fma_f32 v[8:9], v[8:9], v[20:21], v[36:37] op_sel_hi:[1,0,1]
	v_cvt_pk_bf16_f32 v104, v12, v13
	v_cvt_pk_bf16_f32 v105, v14, v15
	v_cvt_pk_bf16_f32 v106, v16, v17
	v_cvt_pk_bf16_f32 v107, v18, v19
	v_cvt_pk_bf16_f32 v92, v4, v5
	v_cvt_pk_bf16_f32 v93, v6, v7
	s_nop 0
	v_cvt_pk_bf16_f32 v94, v8, v9
	v_cvt_pk_bf16_f32 v95, v10, v11
	v_lshl_or_b32 v58, s13, 12, v183
	v_mov_b32_e32 v59, 0
	v_lshl_add_u64 v[60:61], v[138:139], 0, v[58:59]
	v_lshl_add_u64 v[62:63], v[140:141], 0, v[58:59]
	global_load_dwordx4 v[196:199], v[60:61], off
	global_load_dwordx4 v[200:203], v[62:63], off
	global_load_dwordx4 v[204:207], v[60:61], off offset:32
	global_load_dwordx4 v[208:211], v[62:63], off offset:32
	global_load_dwordx4 v[212:215], v[60:61], off offset:64
	global_load_dwordx4 v[216:219], v[62:63], off offset:64
	global_load_dwordx4 v[220:223], v[60:61], off offset:96
	global_load_dwordx4 v[224:227], v[62:63], off offset:96
	global_load_dwordx4 v[228:231], v[60:61], off offset:128
	global_load_dwordx4 v[232:235], v[62:63], off offset:128
	global_load_dwordx4 v[236:239], v[60:61], off offset:160
	global_load_dwordx4 v[240:243], v[62:63], off offset:160
	global_load_dwordx4 v[244:247], v[60:61], off offset:192
	global_load_dwordx4 v[40:43], v[62:63], off offset:192
	global_load_dwordx4 v[44:47], v[60:61], off offset:224
	global_load_dwordx4 v[48:51], v[62:63], off offset:224
	global_load_dword v21, v3, s[58:59] offset:128
	global_load_dword v20, v3, s[36:37] offset:128
	v_lshl_add_u64 v[12:13], v[136:137], 0, v[132:133]
	v_lshl_add_u64 v[22:23], v[134:135], 0, v[132:133]
	global_load_dwordx4 v[4:7], v[12:13], off
	global_load_dwordx4 v[8:11], v[12:13], off offset:16
	s_nop 0
	global_load_dwordx4 v[12:15], v[22:23], off
	global_load_dwordx4 v[16:19], v[22:23], off offset:16
	v_lshl_or_b32 v132, s13, 12, v183
	v_lshl_add_u64 v[22:23], v[138:139], 0, v[132:133]
	s_waitcnt vmcnt(7)
	v_mul_f32_e32 v2, v2, v0
	v_mul_f32_e32 v2, 0x3fb8aa3b, v2
	v_exp_f32_e32 v2, v2
	s_waitcnt vmcnt(5)
	v_mul_f32_e32 v3, v0, v21
	s_waitcnt vmcnt(4)
	v_mul_f32_e32 v25, v0, v20
	v_mul_f32_e32 v3, 0x3fb8aa3b, v3
	v_mul_f32_e32 v25, 0.15915494, v25
	v_exp_f32_e32 v3, v3
	v_sin_f32_e32 v26, v25
	v_cos_f32_e32 v25, v25
	v_mov_b32_e32 v24, v21
	v_mov_b32_e32 v27, v21
	v_mul_f32_e32 v30, v3, v26
	v_fma_f32 v31, v3, v25, -1.0
	v_mov_b32_e32 v29, v20
	v_mov_b32_e32 v26, v30
	v_mov_b32_e32 v28, v31
	v_pk_mul_f32 v[32:33], v[20:21], v[30:31]
	v_pk_mul_f32 v[24:25], v[24:25], v[26:27] op_sel_hi:[0,1]
	v_pk_mul_f32 v[20:21], v[20:21], v[28:29] op_sel_hi:[0,1]
	v_add_f32_e32 v3, v32, v33
	v_add_f32_e32 v21, v25, v21
	v_sub_f32_e32 v24, v24, v20
	v_div_scale_f32 v20, s[0:1], v21, v21, v3
	v_div_scale_f32 v26, s[0:1], v21, v21, v24
	v_rcp_f32_e32 v27, v20
	v_rcp_f32_e32 v28, v26
	v_div_scale_f32 v25, vcc, v3, v21, v3
	v_fma_f32 v30, -v20, v27, 1.0
	v_fma_f32 v31, -v26, v28, 1.0
	v_fmac_f32_e32 v27, v30, v27
	v_div_scale_f32 v29, s[0:1], v24, v21, v24
	v_fmac_f32_e32 v28, v31, v28
	v_mul_f32_e32 v30, v25, v27
	v_mul_f32_e32 v31, v29, v28
	v_fma_f32 v32, -v20, v30, v25
	v_fma_f32 v33, -v26, v31, v29
	v_fmac_f32_e32 v30, v32, v27
	v_fmac_f32_e32 v31, v33, v28
	v_fma_f32 v20, -v20, v30, v25
	v_fma_f32 v25, -v26, v31, v29
	v_div_fmas_f32 v20, v20, v27, v30
	s_mov_b64 vcc, s[0:1]
	v_div_fixup_f32 v20, v20, v21, v3
	v_div_fmas_f32 v3, v25, v28, v31
	v_div_fixup_f32 v24, v3, v21, v24
	s_waitcnt vmcnt(3)
	v_pk_mul_f32 v[26:27], v[4:5], v[24:25] op_sel_hi:[1,0]
	v_pk_mul_f32 v[28:29], v[6:7], v[24:25] op_sel_hi:[1,0]
	s_waitcnt vmcnt(2)
	v_pk_mul_f32 v[30:31], v[8:9], v[24:25] op_sel_hi:[1,0]
	v_pk_mul_f32 v[32:33], v[10:11], v[24:25] op_sel_hi:[1,0]
	s_waitcnt vmcnt(1)
	v_pk_mul_f32 v[34:35], v[12:13], v[24:25] op_sel_hi:[1,0]
	v_pk_mul_f32 v[36:37], v[14:15], v[24:25] op_sel_hi:[1,0]
	s_waitcnt vmcnt(0)
	v_pk_mul_f32 v[38:39], v[16:17], v[24:25] op_sel_hi:[1,0]
	v_pk_mul_f32 v[24:25], v[18:19], v[24:25] op_sel_hi:[1,0]
	v_pk_fma_f32 v[12:13], v[12:13], v[20:21], v[26:27] op_sel_hi:[1,0,1] neg_lo:[0,0,1] neg_hi:[0,0,1]
	v_pk_fma_f32 v[6:7], v[6:7], v[20:21], v[36:37] op_sel_hi:[1,0,1]
	v_pk_fma_f32 v[4:5], v[4:5], v[20:21], v[34:35] op_sel_hi:[1,0,1]
	v_pk_fma_f32 v[10:11], v[10:11], v[20:21], v[24:25] op_sel_hi:[1,0,1]
	v_pk_fma_f32 v[8:9], v[8:9], v[20:21], v[38:39] op_sel_hi:[1,0,1]
	v_cvt_pk_bf16_f32 v116, v12, v13
	v_lshl_add_u64 v[12:13], v[140:141], 0, v[132:133]
	v_pk_fma_f32 v[14:15], v[14:15], v[20:21], v[28:29] op_sel_hi:[1,0,1] neg_lo:[0,0,1] neg_hi:[0,0,1]
	v_pk_fma_f32 v[18:19], v[18:19], v[20:21], v[32:33] op_sel_hi:[1,0,1] neg_lo:[0,0,1] neg_hi:[0,0,1]
	v_pk_fma_f32 v[16:17], v[16:17], v[20:21], v[30:31] op_sel_hi:[1,0,1] neg_lo:[0,0,1] neg_hi:[0,0,1]
	v_cvt_pk_bf16_f32 v117, v14, v15
	s_lshl_b32 s1, s6, 3
	v_cvt_pk_bf16_f32 v118, v16, v17
	v_cvt_pk_bf16_f32 v119, v18, v19
	v_cvt_pk_bf16_f32 v112, v4, v5
	v_cvt_pk_bf16_f32 v113, v6, v7
	v_cvt_pk_bf16_f32 v114, v8, v9
	v_cvt_pk_bf16_f32 v115, v10, v11
	s_and_b32 s15, s1, 0x1800
	v_or_b32_e32 v3, s15, v174
	v_lshlrev_b32_e32 v3, 3, v3
	s_lshl_b32 s0, s6, 4
	v_and_b32_e32 v3, 0xc080, v3
	s_and_b32 s14, s0, 16
	v_or_b32_e32 v3, s16, v3
	v_or_b32_e32 v132, s14, v176
	v_lshl_or_b32 v3, v3, 9, v177
	v_or3_b32 v14, s14, v175, v3
	v_or_b32_e32 v3, v3, v132
	v_lshlrev_b32_e32 v3, 1, v3
	v_lshlrev_b32_e32 v14, 1, v14
	v_or_b32_e32 v15, 16, v3
	v_mul_f32_e32 v0, v0, v1
	v_mul_f32_e32 v1, 0.15915494, v0
	v_cos_f32_e32 v0, v1
	v_sin_f32_e32 v1, v1
	s_mov_b64 s[0:1], 0
	s_mov_b32 s16, 0
	v_pk_mul_f32 v[198:199], v[126:127], v[198:199]
	v_pk_mul_f32 v[196:197], v[124:125], v[196:197]
	v_pk_mul_f32 v[202:203], v[130:131], v[202:203]
	v_pk_mul_f32 v[200:201], v[128:129], v[200:201]
	s_nop 0
	v_cvt_pk_bf16_f32 v64, v196, v200
	v_cvt_pk_bf16_f32 v65, v197, v201
	v_cvt_pk_bf16_f32 v66, v198, v202
	v_cvt_pk_bf16_f32 v67, v199, v203
	v_pk_mul_f32 v[206:207], v[126:127], v[206:207]
	v_pk_mul_f32 v[204:205], v[124:125], v[204:205]
	v_pk_mul_f32 v[210:211], v[130:131], v[210:211]
	v_pk_mul_f32 v[208:209], v[128:129], v[208:209]
	s_nop 0
	v_cvt_pk_bf16_f32 v68, v204, v208
	v_cvt_pk_bf16_f32 v69, v205, v209
	v_cvt_pk_bf16_f32 v70, v206, v210
	v_cvt_pk_bf16_f32 v71, v207, v211
	v_pk_mul_f32 v[214:215], v[126:127], v[214:215]
	v_pk_mul_f32 v[212:213], v[124:125], v[212:213]
	v_pk_mul_f32 v[218:219], v[130:131], v[218:219]
	v_pk_mul_f32 v[216:217], v[128:129], v[216:217]
	s_nop 0
	v_cvt_pk_bf16_f32 v72, v212, v216
	v_cvt_pk_bf16_f32 v73, v213, v217
	v_cvt_pk_bf16_f32 v74, v214, v218
	v_cvt_pk_bf16_f32 v75, v215, v219
	v_pk_mul_f32 v[222:223], v[126:127], v[222:223]
	v_pk_mul_f32 v[220:221], v[124:125], v[220:221]
	v_pk_mul_f32 v[226:227], v[130:131], v[226:227]
	v_pk_mul_f32 v[224:225], v[128:129], v[224:225]
	s_nop 0
	v_cvt_pk_bf16_f32 v76, v220, v224
	v_cvt_pk_bf16_f32 v77, v221, v225
	v_cvt_pk_bf16_f32 v78, v222, v226
	v_cvt_pk_bf16_f32 v79, v223, v227
	v_pk_mul_f32 v[230:231], v[126:127], v[230:231]
	v_pk_mul_f32 v[228:229], v[124:125], v[228:229]
	v_pk_mul_f32 v[234:235], v[130:131], v[234:235]
	v_pk_mul_f32 v[232:233], v[128:129], v[232:233]
	s_nop 0
	v_cvt_pk_bf16_f32 v84, v228, v232
	v_cvt_pk_bf16_f32 v85, v229, v233
	v_cvt_pk_bf16_f32 v86, v230, v234
	v_cvt_pk_bf16_f32 v87, v231, v235
	v_pk_mul_f32 v[238:239], v[126:127], v[238:239]
	v_pk_mul_f32 v[236:237], v[124:125], v[236:237]
	v_pk_mul_f32 v[242:243], v[130:131], v[242:243]
	v_pk_mul_f32 v[240:241], v[128:129], v[240:241]
	s_nop 0
	v_cvt_pk_bf16_f32 v88, v236, v240
	v_cvt_pk_bf16_f32 v89, v237, v241
	v_cvt_pk_bf16_f32 v90, v238, v242
	v_cvt_pk_bf16_f32 v91, v239, v243
	v_pk_mul_f32 v[246:247], v[126:127], v[246:247]
	v_pk_mul_f32 v[244:245], v[124:125], v[244:245]
	v_pk_mul_f32 v[42:43], v[130:131], v[42:43]
	v_pk_mul_f32 v[40:41], v[128:129], v[40:41]
	s_nop 0
	v_cvt_pk_bf16_f32 v96, v244, v40
	v_cvt_pk_bf16_f32 v97, v245, v41
	v_cvt_pk_bf16_f32 v98, v246, v42
	v_cvt_pk_bf16_f32 v99, v247, v43
	v_lshl_add_u64 v[12:13], v[142:143], 0, s[4:5]
	s_bfe_u32 s4, s6, 0x10001
	v_pk_mul_f32 v[46:47], v[126:127], v[46:47]
	v_pk_mul_f32 v[44:45], v[124:125], v[44:45]
	v_pk_mul_f32 v[50:51], v[130:131], v[50:51]
	v_pk_mul_f32 v[48:49], v[128:129], v[48:49]
	s_nop 0
	v_cvt_pk_bf16_f32 v108, v44, v48
	v_cvt_pk_bf16_f32 v109, v45, v49
	v_cvt_pk_bf16_f32 v110, v46, v50
	v_cvt_pk_bf16_f32 v111, v47, v51
	global_load_dwordx4 v[100:103], v[12:13], off
	global_load_dwordx4 v[80:83], v[12:13], off offset:32
	global_load_dwordx4 v[120:123], v14, s[54:55]
	global_load_dwordx2 v[158:159], v3, s[54:55]
	global_load_dwordx2 v[156:157], v15, s[54:55]
	v_or_b32_e32 v3, s2, v174
	v_pk_mul_f32 v[160:161], v[0:1], v[2:3] op_sel_hi:[1,0]
	v_lshrrev_b32_e32 v187, 3, v3
	v_pk_mov_b32 v[162:163], v[160:161], v[160:161] op_sel:[1,0]
	v_mov_b32_e32 v164, v160
	v_mov_b32_e32 v165, v160
	v_mov_b32_e32 v166, v161
	v_mov_b32_e32 v167, v161
	s_waitcnt vmcnt(0)

	.amdhsa_kernel _Z14fwd_megakernel4Args
		.amdhsa_group_segment_fixed_size 0
		.amdhsa_private_segment_fixed_size 0
		.amdhsa_kernarg_size 416
		.amdhsa_user_sgpr_count 2
		.amdhsa_user_sgpr_dispatch_ptr 0
		.amdhsa_user_sgpr_queue_ptr 0
		.amdhsa_user_sgpr_kernarg_segment_ptr 1
		.amdhsa_user_sgpr_dispatch_id 0
		.amdhsa_user_sgpr_kernarg_preload_length 0
		.amdhsa_user_sgpr_kernarg_preload_offset 0
		.amdhsa_user_sgpr_private_segment_size 0
		.amdhsa_uses_dynamic_stack 0
		.amdhsa_enable_private_segment 0
		.amdhsa_system_sgpr_workgroup_id_x 1
		.amdhsa_system_sgpr_workgroup_id_y 0
		.amdhsa_system_sgpr_workgroup_id_z 0
		.amdhsa_system_sgpr_workgroup_info 0
		.amdhsa_system_vgpr_workitem_id 2
		.amdhsa_next_free_vgpr 256
		.amdhsa_next_free_sgpr 98
		.amdhsa_accum_offset 256
		.amdhsa_reserve_vcc 1
		.amdhsa_float_round_mode_32 0
		.amdhsa_float_round_mode_16_64 0
		.amdhsa_float_denorm_mode_32 3
		.amdhsa_float_denorm_mode_16_64 3
		.amdhsa_dx10_clamp 1
		.amdhsa_ieee_mode 1
		.amdhsa_fp16_overflow 0
		.amdhsa_tg_split 0
		.amdhsa_exception_fp_ieee_invalid_op 0
		.amdhsa_exception_fp_denorm_src 0
		.amdhsa_exception_fp_ieee_div_zero 0
		.amdhsa_exception_fp_ieee_overflow 0
		.amdhsa_exception_fp_ieee_underflow 0
		.amdhsa_exception_fp_ieee_inexact 0
		.amdhsa_exception_int_div_zero 0
	.end_amdhsa_kernel

amdhsa.kernels:
  - .agpr_count:     0
    .args:
      - .offset:         0
        .size:           160
        .value_kind:     by_value
      - .offset:         160
        .size:           4
        .value_kind:     hidden_block_count_x
      - .offset:         164
        .size:           4
        .value_kind:     hidden_block_count_y
      - .offset:         168
        .size:           4
        .value_kind:     hidden_block_count_z
      - .offset:         172
        .size:           2
        .value_kind:     hidden_group_size_x
      - .offset:         174
        .size:           2
        .value_kind:     hidden_group_size_y
      - .offset:         176
        .size:           2
        .value_kind:     hidden_group_size_z
      - .offset:         178
        .size:           2
        .value_kind:     hidden_remainder_x
      - .offset:         180
        .size:           2
        .value_kind:     hidden_remainder_y
      - .offset:         182
        .size:           2
        .value_kind:     hidden_remainder_z
      - .offset:         200
        .size:           8
        .value_kind:     hidden_global_offset_x
      - .offset:         208
        .size:           8
        .value_kind:     hidden_global_offset_y
      - .offset:         216
        .size:           8
        .value_kind:     hidden_global_offset_z
      - .offset:         224
        .size:           2
        .value_kind:     hidden_grid_dims
      - .offset:         248
        .size:           8
        .value_kind:     hidden_multigrid_sync_arg
      - .offset:         280
        .size:           4
        .value_kind:     hidden_dynamic_lds_size
    .group_segment_fixed_size: 0
    .kernarg_segment_align: 8
    .kernarg_segment_size: 416
    .language:       OpenCL C
    .language_version:
      - 2
      - 0
    .max_flat_workgroup_size: 512
    .name:           _Z14fwd_megakernel4Args
    .private_segment_fixed_size: 0
    .sgpr_count:     104
    .sgpr_spill_count: 54
    .symbol:         _Z14fwd_megakernel4Args.kd
    .uniform_work_group_size: 1
    .uses_dynamic_stack: false
    .vgpr_count:     256
    .vgpr_spill_count: 0
    .wavefront_size: 64
